# grid barriers: waiting workgroups back off longer between polls of the TOP counter (s_sleep 4) to keep the line free for the leaders' adds
# speedup vs baseline: 1.0025x; 1.0025x over previous
.LBB0_153:
	s_and_b32 s15, s14, 0xff
	s_mov_b64 s[46:47], -1
	s_cmp_lg_u32 s15, 0
	s_mov_b64 s[52:53], -1
	s_sleep 4
	s_cbranch_scc1 .LBB0_156
	global_load_dword v2, v0, s[12:13] sc1
	s_waitcnt vmcnt(0)
	v_cmp_eq_u32_e32 vcc, 0, v2
	s_cbranch_vccnz .LBB0_158
	s_mov_b64 s[52:53], 0
	s_mov_b64 s[48:49], -1

.LBB0_246:
	s_and_b32 s15, s14, 0xff
	s_mov_b64 s[28:29], -1
	s_cmp_lg_u32 s15, 0
	s_mov_b64 s[48:49], -1
	s_sleep 4
	s_cbranch_scc1 .LBB0_249
	global_load_dword v2, v0, s[10:11] sc1
	s_waitcnt vmcnt(0)
	v_cmp_eq_u32_e32 vcc, 0, v2
	s_cbranch_vccnz .LBB0_251
	s_mov_b64 s[48:49], 0
	s_mov_b64 s[46:47], -1

.LBB0_313:
	s_and_b32 s15, s14, 0xff
	s_mov_b64 s[24:25], -1
	s_cmp_lg_u32 s15, 0
	s_mov_b64 s[28:29], -1
	s_sleep 4
	s_cbranch_scc1 .LBB0_316
	global_load_dword v2, v0, s[12:13] sc1
	s_waitcnt vmcnt(0)
	v_cmp_eq_u32_e32 vcc, 0, v2
	s_cbranch_vccnz .LBB0_318
	s_mov_b64 s[28:29], 0
	s_mov_b64 s[26:27], -1

.LBB0_789:
	s_and_b32 s24, s3, 0xff
	s_mov_b64 s[22:23], -1
	s_cmp_lg_u32 s24, 0
	s_mov_b64 s[26:27], -1
	s_sleep 4
	s_cbranch_scc1 .LBB0_792
	global_load_dword v2, v0, s[12:13] sc1
	s_waitcnt vmcnt(0)
	v_cmp_eq_u32_e32 vcc, 0, v2
	s_cbranch_vccnz .LBB0_794
	s_mov_b64 s[26:27], 0
	s_mov_b64 s[24:25], -1
